# grid barriers: L1 invalidate issued right behind the arrival atomic (not delaying the arrival), none on the way out
# baseline (speedup 1.0000x reference)
.LBB0_221:
	s_or_b64 exec, exec, s[10:11]
	v_cvt_f32_u32_e32 v5, v3
	s_waitcnt vmcnt(0)
	buffer_inv sc1
	v_readfirstlane_b32 s8, v4
	v_sub_u32_e32 v4, 0, v3
	v_rcp_iflag_f32_e32 v5, v5
	v_add_u32_e32 v6, s8, v2
	v_mul_f32_e32 v5, 0x4f7ffffe, v5
	v_cvt_u32_f32_e32 v5, v5
	v_mul_lo_u32 v2, v4, v5
	v_mul_hi_u32 v2, v5, v2
	v_add_u32_e32 v2, v5, v2
	v_mul_hi_u32 v2, v6, v2
	v_mul_lo_u32 v4, v2, v3
	v_sub_u32_e32 v4, v6, v4
	v_add_u32_e32 v5, 1, v2
	v_cmp_ge_u32_e32 vcc, v4, v3
	s_nop 1
	v_cndmask_b32_e32 v2, v2, v5, vcc
	v_sub_u32_e32 v5, v4, v3
	v_cndmask_b32_e32 v4, v4, v5, vcc
	v_add_u32_e32 v5, 1, v2
	v_cmp_ge_u32_e32 vcc, v4, v3
	v_add_u32_e32 v4, 1, v6
	s_nop 0
	v_cndmask_b32_e32 v2, v2, v5, vcc
	v_mul_lo_u32 v5, v3, v2
	v_add_u32_e32 v3, v5, v3
	v_cmp_ne_u32_e32 vcc, v4, v3
	s_and_saveexec_b64 s[8:9], vcc
	s_xor_b64 s[8:9], exec, s[8:9]
	s_cbranch_execz .LBB0_235
	s_add_i32 s10, s26, 0x900
	s_mov_b32 s11, 0
	s_lshl_b64 s[10:11], s[10:11], 2
	s_add_u32 s14, s2, s10
	s_addc_u32 s15, s3, s11
	s_waitcnt lgkmcnt(0)
	v_mov_b32_e32 v1, 0
	global_load_dword v3, v1, s[14:15] sc1
	s_waitcnt vmcnt(0)
	v_cmp_eq_u32_e32 vcc, v3, v2
	s_and_saveexec_b64 s[10:11], vcc
	s_cbranch_execz .LBB0_234
	s_add_u32 s12, s6, 0x4200
	s_addc_u32 s13, s7, 0
	s_mov_b32 s27, 1
	s_mov_b64 s[16:17], 0
	s_branch .LBB0_225

.LBB0_303:
	s_or_b64 exec, exec, s[14:15]
	v_cvt_f32_u32_e32 v7, v5
	s_waitcnt vmcnt(0)
	buffer_inv sc1
	v_readfirstlane_b32 s10, v6
	v_sub_u32_e32 v6, 0, v5
	v_rcp_iflag_f32_e32 v7, v7
	v_add_u32_e32 v8, s10, v2
	v_mul_f32_e32 v7, 0x4f7ffffe, v7
	v_cvt_u32_f32_e32 v7, v7
	v_mul_lo_u32 v2, v6, v7
	v_mul_hi_u32 v2, v7, v2
	v_add_u32_e32 v2, v7, v2
	v_mul_hi_u32 v2, v8, v2
	v_mul_lo_u32 v6, v2, v5
	v_sub_u32_e32 v6, v8, v6
	v_add_u32_e32 v7, 1, v2
	v_cmp_ge_u32_e32 vcc, v6, v5
	s_nop 1
	v_cndmask_b32_e32 v2, v2, v7, vcc
	v_sub_u32_e32 v7, v6, v5
	v_cndmask_b32_e32 v6, v6, v7, vcc
	v_add_u32_e32 v7, 1, v2
	v_cmp_ge_u32_e32 vcc, v6, v5
	v_add_u32_e32 v6, 1, v8
	s_nop 0
	v_cndmask_b32_e32 v2, v2, v7, vcc
	v_mul_lo_u32 v7, v5, v2
	v_add_u32_e32 v5, v7, v5
	v_cmp_ne_u32_e32 vcc, v6, v5
	s_and_saveexec_b64 s[10:11], vcc
	s_xor_b64 s[10:11], exec, s[10:11]
	s_cbranch_execz .LBB0_317
	s_add_i32 s40, s37, 0x900
	s_lshl_b64 s[14:15], s[40:41], 2
	s_add_u32 s20, s35, s14
	s_addc_u32 s21, s36, s15
	s_waitcnt lgkmcnt(0)
	global_load_dword v4, v3, s[20:21] sc1
	s_waitcnt vmcnt(0)
	v_cmp_eq_u32_e32 vcc, v4, v2
	s_and_saveexec_b64 s[14:15], vcc
	s_cbranch_execz .LBB0_316
	s_add_u32 s18, s8, 0x4200
	s_addc_u32 s19, s9, 0
	s_mov_b32 s40, 1
	s_mov_b64 s[22:23], 0
	s_branch .LBB0_307

.LBB0_461:
	s_or_b64 exec, exec, s[14:15]
	v_cvt_f32_u32_e32 v7, v5
	s_waitcnt vmcnt(0)
	buffer_inv sc1
	v_readfirstlane_b32 s10, v6
	v_sub_u32_e32 v6, 0, v5
	v_rcp_iflag_f32_e32 v7, v7
	v_add_u32_e32 v8, s10, v2
	v_mul_f32_e32 v7, 0x4f7ffffe, v7
	v_cvt_u32_f32_e32 v7, v7
	v_mul_lo_u32 v2, v6, v7
	v_mul_hi_u32 v2, v7, v2
	v_add_u32_e32 v2, v7, v2
	v_mul_hi_u32 v2, v8, v2
	v_mul_lo_u32 v6, v2, v5
	v_sub_u32_e32 v6, v8, v6
	v_add_u32_e32 v7, 1, v2
	v_cmp_ge_u32_e32 vcc, v6, v5
	s_nop 1
	v_cndmask_b32_e32 v2, v2, v7, vcc
	v_sub_u32_e32 v7, v6, v5
	v_cndmask_b32_e32 v6, v6, v7, vcc
	v_add_u32_e32 v7, 1, v2
	v_cmp_ge_u32_e32 vcc, v6, v5
	v_add_u32_e32 v6, 1, v8
	s_nop 0
	v_cndmask_b32_e32 v2, v2, v7, vcc
	v_mul_lo_u32 v7, v5, v2
	v_add_u32_e32 v5, v7, v5
	v_cmp_ne_u32_e32 vcc, v6, v5
	s_and_saveexec_b64 s[10:11], vcc
	s_xor_b64 s[10:11], exec, s[10:11]
	s_cbranch_execz .LBB0_475
	s_add_i32 s40, s36, 0x900
	s_lshl_b64 s[14:15], s[40:41], 2
	s_add_u32 s20, s17, s14
	s_addc_u32 s21, s35, s15
	s_waitcnt lgkmcnt(0)
	global_load_dword v4, v3, s[20:21] sc1
	s_waitcnt vmcnt(0)
	v_cmp_eq_u32_e32 vcc, v4, v2
	s_and_saveexec_b64 s[14:15], vcc
	s_cbranch_execz .LBB0_474
	s_add_u32 s18, s8, 0x4200
	s_addc_u32 s19, s9, 0
	s_mov_b32 s37, 1
	s_mov_b64 s[22:23], 0
	s_branch .LBB0_465

.LBB0_527:
	s_or_b64 exec, exec, s[10:11]
	v_cvt_f32_u32_e32 v7, v5
	s_waitcnt vmcnt(0)
	buffer_inv sc1
	v_readfirstlane_b32 s8, v6
	v_sub_u32_e32 v6, 0, v5
	v_rcp_iflag_f32_e32 v7, v7
	v_add_u32_e32 v8, s8, v2
	v_mul_f32_e32 v7, 0x4f7ffffe, v7
	v_cvt_u32_f32_e32 v7, v7
	v_mul_lo_u32 v2, v6, v7
	v_mul_hi_u32 v2, v7, v2
	v_add_u32_e32 v2, v7, v2
	v_mul_hi_u32 v2, v8, v2
	v_mul_lo_u32 v6, v2, v5
	v_sub_u32_e32 v6, v8, v6
	v_add_u32_e32 v7, 1, v2
	v_cmp_ge_u32_e32 vcc, v6, v5
	s_nop 1
	v_cndmask_b32_e32 v2, v2, v7, vcc
	v_sub_u32_e32 v7, v6, v5
	v_cndmask_b32_e32 v6, v6, v7, vcc
	v_add_u32_e32 v7, 1, v2
	v_cmp_ge_u32_e32 vcc, v6, v5
	v_add_u32_e32 v6, 1, v8
	s_nop 0
	v_cndmask_b32_e32 v2, v2, v7, vcc
	v_mul_lo_u32 v7, v5, v2
	v_add_u32_e32 v5, v7, v5
	v_cmp_ne_u32_e32 vcc, v6, v5
	s_and_saveexec_b64 s[8:9], vcc
	s_xor_b64 s[8:9], exec, s[8:9]
	s_cbranch_execz .LBB0_541
	s_add_i32 s40, s34, 0x900
	s_lshl_b64 s[10:11], s[40:41], 2
	s_add_u32 s18, s30, s10
	s_addc_u32 s19, s31, s11
	s_waitcnt lgkmcnt(0)
	global_load_dword v4, v3, s[18:19] sc1
	s_waitcnt vmcnt(0)
	v_cmp_eq_u32_e32 vcc, v4, v2
	s_and_saveexec_b64 s[10:11], vcc
	s_cbranch_execz .LBB0_540
	s_add_u32 s14, s6, 0x4200
	s_addc_u32 s15, s7, 0
	s_mov_b32 s35, 1
	s_mov_b64 s[20:21], 0
	s_branch .LBB0_531

.LBB0_1297:
	s_or_b64 exec, exec, s[6:7]
	v_cvt_f32_u32_e32 v4, v2
	s_waitcnt vmcnt(0)
	buffer_inv sc1
	v_readfirstlane_b32 s4, v3
	v_sub_u32_e32 v3, 0, v2
	v_rcp_iflag_f32_e32 v4, v4
	v_add_u32_e32 v5, s4, v1
	v_mul_f32_e32 v4, 0x4f7ffffe, v4
	v_cvt_u32_f32_e32 v4, v4
	v_mul_lo_u32 v1, v3, v4
	v_mul_hi_u32 v1, v4, v1
	v_add_u32_e32 v1, v4, v1
	v_mul_hi_u32 v1, v5, v1
	v_mul_lo_u32 v3, v1, v2
	v_sub_u32_e32 v3, v5, v3
	v_add_u32_e32 v4, 1, v1
	v_cmp_ge_u32_e32 vcc, v3, v2
	s_nop 1
	v_cndmask_b32_e32 v1, v1, v4, vcc
	v_sub_u32_e32 v4, v3, v2
	v_cndmask_b32_e32 v3, v3, v4, vcc
	v_add_u32_e32 v4, 1, v1
	v_cmp_ge_u32_e32 vcc, v3, v2
	v_add_u32_e32 v3, 1, v5
	s_nop 0
	v_cndmask_b32_e32 v1, v1, v4, vcc
	v_mul_lo_u32 v4, v2, v1
	v_add_u32_e32 v2, v4, v2
	v_cmp_ne_u32_e32 vcc, v3, v2
	s_and_saveexec_b64 s[4:5], vcc
	s_xor_b64 s[4:5], exec, s[4:5]
	s_cbranch_execz .LBB0_1311
	s_add_i32 s6, s24, 0x900
	s_mov_b32 s7, 0
	s_lshl_b64 s[6:7], s[6:7], 2
	s_add_u32 s10, s22, s6
	s_addc_u32 s11, s23, s7
	s_waitcnt lgkmcnt(0)
	v_mov_b32_e32 v0, 0
	global_load_dword v2, v0, s[10:11] sc1
	s_waitcnt vmcnt(0)
	v_cmp_eq_u32_e32 vcc, v2, v1
	s_and_saveexec_b64 s[6:7], vcc
	s_cbranch_execz .LBB0_1310
	s_add_u32 s8, s0, 0x4200
	s_addc_u32 s9, s1, 0
	s_mov_b32 s25, 1
	s_mov_b64 s[12:13], 0
	s_branch .LBB0_1301
